# EpiRes epilogue: second-half residual loads issued with the first half (one counted wait), on top of v004
# baseline (speedup 1.0000x reference)
; DI void store8(bf16_t* p, f32x4 a, f32x4 b) { u32x4 w; w.x = pk(a[0], a[1]); w.y = pk(a[2], a[3]); w.z = pk(b[0], b[1]); w.w = pk(b[2], b[3]); *(u32x4*)p = w; }
; DI void unpk8(const u32x4 w, f32x4& a, f32x4& b) { a = (f32x4){bflo(w.x), bfhi(w.x), bflo(w.y), bfhi(w.y)}; b = (f32x4){bflo(w.z), bfhi(w.z), bflo(w.w), bfhi(w.w)}; }
;     DI void operator()(AccRef acc, const Unit& u, int wr, int wc, int, int) const {
;     ...
;         int row0 = u.pm * 256 + wr * 64 + fr; asm volatile("" : "+v"(row0)); int col0 = u.pn * 256 + wc * 32 + 8 * fq; asm volatile("" : "+v"(col0));
; #pragma unroll
;         for (int ai = 0; ai < 2; ++ai) {
;             u32x4 px[4][2];
; #pragma unroll
;             for (int m = 0; m < 4; ++m)
; #pragma unroll
;                 for (int bj = 0; bj < 2; ++bj) px[m][bj] = *(const u32x4*)(X + (size_t)(row0 + ai * 128 + m * 16) * D + col0 + bj * 128);
; #pragma unroll
;             for (int m = 0; m < 4; ++m)
; #pragma unroll
;                 for (int bj = 0; bj < 2; ++bj) { f32x4 x0, x1; unpk8(px[m][bj], x0, x1);
;                     store8(Z + (size_t)(row0 + ai * 128 + m * 16) * D + col0 + bj * 128, x0 * DN_ALPHA + acc[ai][bj][m][0] * s, x1 * DN_ALPHA + acc[ai][bj][m][1] * s); }
.LBB0_687:
	s_lshl_b32 s43, s43, 8
	v_mbcnt_lo_u32_b32 v131, -1, 0
	v_mbcnt_hi_u32_b32 v131, -1, v131
	s_add_i32 s43, s43, s21
	v_and_or_b32 v130, v131, 15, s43
	s_lshl_b32 s4, s4, 8
	v_ashrrev_i32_e32 v131, 1, v131
	s_or_b32 s4, s4, s24
	v_and_b32_e32 v131, -8, v131
	v_add_u32_e32 v132, s4, v131
	v_readlane_b32 s92, v250, 0
	v_ashrrev_i32_e32 v133, 31, v132
	v_lshlrev_b64 v[164:165], 1, v[132:133]
	v_readlane_b32 s94, v250, 2
	v_readlane_b32 s95, v250, 3
	v_ashrrev_i32_e32 v131, 31, v130
	v_lshlrev_b64 v[168:169], 11, v[130:131]
	v_lshl_add_u64 v[166:167], s[94:95], 0, v[164:165]
	v_lshl_add_u64 v[130:131], v[166:167], 0, v[168:169]
	global_load_dwordx4 v[184:187], v[130:131], off
	global_load_dwordx4 v[188:191], v[130:131], off offset:256
	s_mov_b64 s[86:87], 0x8000
	v_lshl_add_u64 v[174:175], v[168:169], 0, s[86:87]
	v_lshl_add_u64 v[130:131], v[166:167], 0, v[174:175]
	global_load_dwordx4 v[192:195], v[130:131], off
	global_load_dwordx4 v[146:149], v[130:131], off offset:256
	s_mov_b64 s[86:87], 0x10000
	v_lshl_add_u64 v[172:173], v[168:169], 0, s[86:87]
	v_lshl_add_u64 v[130:131], v[166:167], 0, v[172:173]
	global_load_dwordx4 v[142:145], v[130:131], off
	global_load_dwordx4 v[138:141], v[130:131], off offset:256
	s_mov_b64 s[86:87], 0x18000
	v_lshl_add_u64 v[170:171], v[168:169], 0, s[86:87]
	v_lshl_add_u64 v[130:131], v[166:167], 0, v[170:171]
	global_load_dwordx4 v[134:137], v[130:131], off
	s_nop 0
	global_load_dwordx4 v[130:133], v[130:131], off offset:256
	s_mov_b64 s[86:87], 0x40000
	v_lshl_add_u64 v[212:213], v[168:169], 0, s[86:87]
	v_lshl_add_u64 v[212:213], v[166:167], 0, v[212:213]
	global_load_dwordx4 v[230:233], v[212:213], off
	global_load_dwordx4 v[234:237], v[212:213], off offset:256
	s_mov_b64 s[86:87], 0x48000
	v_lshl_add_u64 v[212:213], v[168:169], 0, s[86:87]
	v_lshl_add_u64 v[212:213], v[166:167], 0, v[212:213]
	global_load_dwordx4 v[238:241], v[212:213], off
	global_load_dwordx4 v[242:245], v[212:213], off offset:256
	s_mov_b64 s[86:87], 0x50000
	v_lshl_add_u64 v[212:213], v[168:169], 0, s[86:87]
	v_lshl_add_u64 v[212:213], v[166:167], 0, v[212:213]
	global_load_dwordx4 v[246:249], v[212:213], off
	global_load_dwordx4 v[208:211], v[212:213], off offset:256
	s_mov_b64 s[86:87], 0x58000
	v_lshl_add_u64 v[212:213], v[168:169], 0, s[86:87]
	v_lshl_add_u64 v[212:213], v[166:167], 0, v[212:213]
	global_load_dwordx4 v[196:199], v[212:213], off
	global_load_dwordx4 v[200:203], v[212:213], off offset:256
	v_mov_b32_e32 v157, v156
	s_mov_b64 s[86:87], 0x48000
	s_and_b64 vcc, exec, s[36:37]
	s_mov_b32 s95, s52
	v_readlane_b32 s93, v250, 1
	s_waitcnt vmcnt(8)
	v_lshlrev_b32_e32 v178, 16, v184
	v_and_b32_e32 v179, 0xffff0000, v184
	v_lshlrev_b32_e32 v180, 16, v185
	v_and_b32_e32 v181, 0xffff0000, v185
	v_lshlrev_b32_e32 v182, 16, v186
	v_and_b32_e32 v183, 0xffff0000, v186
	v_lshlrev_b32_e32 v184, 16, v187
	v_and_b32_e32 v185, 0xffff0000, v187
	v_pk_mul_f32 v[178:179], v[178:179], s[16:17] op_sel_hi:[1,0]
	v_pk_mul_f32 v[180:181], v[180:181], s[16:17] op_sel_hi:[1,0]
	v_pk_fma_f32 v[126:127], v[158:159], v[126:127], v[178:179]
	v_pk_fma_f32 v[128:129], v[156:157], v[128:129], v[180:181]
	v_pk_mul_f32 v[178:179], v[182:183], s[16:17] op_sel_hi:[1,0]
	v_pk_mul_f32 v[180:181], v[184:185], s[16:17] op_sel_hi:[1,0]
	v_lshl_add_u64 v[186:187], s[46:47], 0, v[168:169]
	v_pk_fma_f32 v[180:181], v[156:157], v[124:125], v[180:181]
	v_pk_fma_f32 v[124:125], v[158:159], v[122:123], v[178:179]
	v_lshl_add_u64 v[186:187], v[186:187], 0, v[164:165]
	v_cvt_pk_bf16_f32 v122, v126, v127
	v_cvt_pk_bf16_f32 v123, v128, v129
	v_cvt_pk_bf16_f32 v124, v124, v125
	v_cvt_pk_bf16_f32 v125, v180, v181
	global_store_dwordx4 v[186:187], v[122:125], off
	v_lshlrev_b32_e32 v126, 16, v190
	v_and_b32_e32 v127, 0xffff0000, v190
	v_lshlrev_b32_e32 v122, 16, v188
	v_and_b32_e32 v123, 0xffff0000, v188
	v_lshlrev_b32_e32 v124, 16, v189
	v_and_b32_e32 v125, 0xffff0000, v189
	v_lshlrev_b32_e32 v128, 16, v191
	v_and_b32_e32 v129, 0xffff0000, v191
	v_pk_mul_f32 v[122:123], v[122:123], s[16:17] op_sel_hi:[1,0]
	v_pk_mul_f32 v[124:125], v[124:125], s[16:17] op_sel_hi:[1,0]
	v_pk_fma_f32 v[118:119], v[158:159], v[118:119], v[122:123]
	v_pk_fma_f32 v[120:121], v[156:157], v[120:121], v[124:125]
	v_pk_mul_f32 v[122:123], v[126:127], s[16:17] op_sel_hi:[1,0]
	v_pk_mul_f32 v[124:125], v[128:129], s[16:17] op_sel_hi:[1,0]
	s_nop 0
	v_pk_fma_f32 v[124:125], v[156:157], v[116:117], v[124:125]
	v_pk_fma_f32 v[116:117], v[158:159], v[114:115], v[122:123]
	v_cvt_pk_bf16_f32 v114, v118, v119
	v_cvt_pk_bf16_f32 v115, v120, v121
	v_lshlrev_b32_e32 v120, 16, v192
	v_cvt_pk_bf16_f32 v116, v116, v117
	v_cvt_pk_bf16_f32 v117, v124, v125
	global_store_dwordx4 v[186:187], v[114:117], off offset:256
	v_and_b32_e32 v121, 0xffff0000, v192
	v_lshlrev_b32_e32 v118, 16, v193
	v_lshlrev_b32_e32 v116, 16, v194
	v_and_b32_e32 v117, 0xffff0000, v194
	v_lshlrev_b32_e32 v114, 16, v195
	v_and_b32_e32 v115, 0xffff0000, v195
	v_and_b32_e32 v119, 0xffff0000, v193
	v_pk_mul_f32 v[116:117], v[116:117], s[16:17] op_sel_hi:[1,0]
	v_pk_mul_f32 v[114:115], v[114:115], s[16:17] op_sel_hi:[1,0]
	v_lshl_add_u64 v[122:123], s[46:47], 0, v[174:175]
	v_pk_mul_f32 v[120:121], v[120:121], s[16:17] op_sel_hi:[1,0]
	v_pk_mul_f32 v[118:119], v[118:119], s[16:17] op_sel_hi:[1,0]
	v_pk_fma_f32 v[114:115], v[156:157], v[108:109], v[114:115]
	v_pk_fma_f32 v[108:109], v[158:159], v[106:107], v[116:117]
	v_lshl_add_u64 v[122:123], v[122:123], 0, v[164:165]
	v_pk_fma_f32 v[112:113], v[156:157], v[112:113], v[118:119]
	v_pk_fma_f32 v[110:111], v[158:159], v[110:111], v[120:121]
	s_nop 0
	v_cvt_pk_bf16_f32 v106, v110, v111
; DI void store8(bf16_t* p, f32x4 a, f32x4 b) { u32x4 w; w.x = pk(a[0], a[1]); w.y = pk(a[2], a[3]); w.z = pk(b[0], b[1]); w.w = pk(b[2], b[3]); *(u32x4*)p = w; }
; DI void unpk8(const u32x4 w, f32x4& a, f32x4& b) { a = (f32x4){bflo(w.x), bfhi(w.x), bflo(w.y), bfhi(w.y)}; b = (f32x4){bflo(w.z), bfhi(w.z), bflo(w.w), bfhi(w.w)}; }
;     DI void operator()(AccRef acc, const Unit& u, int wr, int wc, int, int) const {
;     ...
;                 for (int bj = 0; bj < 2; ++bj) px[m][bj] = *(const u32x4*)(X + (size_t)(row0 + ai * 128 + m * 16) * D + col0 + bj * 128);
; #pragma unroll
;             for (int m = 0; m < 4; ++m)
; #pragma unroll
;                 for (int bj = 0; bj < 2; ++bj) { f32x4 x0, x1; unpk8(px[m][bj], x0, x1);
;                     store8(Z + (size_t)(row0 + ai * 128 + m * 16) * D + col0 + bj * 128, x0 * DN_ALPHA + acc[ai][bj][m][0] * s, x1 * DN_ALPHA + acc[ai][bj][m][1] * s); }
	v_cvt_pk_bf16_f32 v107, v112, v113
	v_cvt_pk_bf16_f32 v108, v108, v109
	v_cvt_pk_bf16_f32 v109, v114, v115
	global_store_dwordx4 v[122:123], v[106:109], off
	v_lshlrev_b32_e32 v110, 16, v148
	v_and_b32_e32 v111, 0xffff0000, v148
	v_lshlrev_b32_e32 v106, 16, v146
	v_and_b32_e32 v107, 0xffff0000, v146
	v_lshlrev_b32_e32 v108, 16, v147
	v_and_b32_e32 v109, 0xffff0000, v147
	v_lshlrev_b32_e32 v112, 16, v149
	v_and_b32_e32 v113, 0xffff0000, v149
	v_pk_mul_f32 v[106:107], v[106:107], s[16:17] op_sel_hi:[1,0]
	v_pk_mul_f32 v[108:109], v[108:109], s[16:17] op_sel_hi:[1,0]
	v_pk_fma_f32 v[102:103], v[158:159], v[102:103], v[106:107]
	v_pk_fma_f32 v[104:105], v[156:157], v[104:105], v[108:109]
	v_pk_mul_f32 v[106:107], v[110:111], s[16:17] op_sel_hi:[1,0]
	v_pk_mul_f32 v[108:109], v[112:113], s[16:17] op_sel_hi:[1,0]
	s_nop 0
	v_pk_fma_f32 v[108:109], v[156:157], v[100:101], v[108:109]
	v_pk_fma_f32 v[100:101], v[158:159], v[98:99], v[106:107]
	v_cvt_pk_bf16_f32 v98, v102, v103
	v_cvt_pk_bf16_f32 v99, v104, v105
	v_lshlrev_b32_e32 v102, 16, v144
	v_cvt_pk_bf16_f32 v100, v100, v101
	v_cvt_pk_bf16_f32 v101, v108, v109
	global_store_dwordx4 v[122:123], v[98:101], off offset:256
	v_and_b32_e32 v103, 0xffff0000, v144
	v_lshlrev_b32_e32 v104, 16, v145
	v_lshlrev_b32_e32 v98, 16, v142
	v_and_b32_e32 v99, 0xffff0000, v142
	v_lshlrev_b32_e32 v100, 16, v143
	v_and_b32_e32 v101, 0xffff0000, v143
	v_and_b32_e32 v105, 0xffff0000, v145
	v_pk_mul_f32 v[98:99], v[98:99], s[16:17] op_sel_hi:[1,0]
	v_pk_mul_f32 v[100:101], v[100:101], s[16:17] op_sel_hi:[1,0]
	v_pk_fma_f32 v[94:95], v[158:159], v[94:95], v[98:99]
	v_pk_fma_f32 v[96:97], v[156:157], v[96:97], v[100:101]
	v_pk_mul_f32 v[98:99], v[102:103], s[16:17] op_sel_hi:[1,0]
	v_pk_mul_f32 v[100:101], v[104:105], s[16:17] op_sel_hi:[1,0]
	v_lshl_add_u64 v[106:107], s[46:47], 0, v[172:173]
	v_pk_fma_f32 v[100:101], v[156:157], v[92:93], v[100:101]
	v_pk_fma_f32 v[92:93], v[158:159], v[90:91], v[98:99]
	v_lshl_add_u64 v[106:107], v[106:107], 0, v[164:165]
	v_cvt_pk_bf16_f32 v90, v94, v95
	v_cvt_pk_bf16_f32 v91, v96, v97
	v_cvt_pk_bf16_f32 v92, v92, v93
	v_cvt_pk_bf16_f32 v93, v100, v101
	global_store_dwordx4 v[106:107], v[90:93], off
	v_lshlrev_b32_e32 v94, 16, v140
	v_and_b32_e32 v95, 0xffff0000, v140
	v_lshlrev_b32_e32 v90, 16, v138
	v_and_b32_e32 v91, 0xffff0000, v138
	v_lshlrev_b32_e32 v92, 16, v139
	v_and_b32_e32 v93, 0xffff0000, v139
	v_lshlrev_b32_e32 v96, 16, v141
	v_and_b32_e32 v97, 0xffff0000, v141
	v_pk_mul_f32 v[90:91], v[90:91], s[16:17] op_sel_hi:[1,0]
	v_pk_mul_f32 v[92:93], v[92:93], s[16:17] op_sel_hi:[1,0]
	v_pk_fma_f32 v[86:87], v[158:159], v[86:87], v[90:91]
	v_pk_fma_f32 v[88:89], v[156:157], v[88:89], v[92:93]
	v_pk_mul_f32 v[90:91], v[94:95], s[16:17] op_sel_hi:[1,0]
	v_pk_mul_f32 v[92:93], v[96:97], s[16:17] op_sel_hi:[1,0]
	v_lshl_add_u64 v[100:101], v[168:169], 0, s[48:49]
	v_pk_fma_f32 v[92:93], v[156:157], v[84:85], v[92:93]
	v_pk_fma_f32 v[84:85], v[158:159], v[82:83], v[90:91]
	v_cvt_pk_bf16_f32 v82, v86, v87
	v_cvt_pk_bf16_f32 v83, v88, v89
	v_lshlrev_b32_e32 v86, 16, v136
	v_cvt_pk_bf16_f32 v84, v84, v85
	v_cvt_pk_bf16_f32 v85, v92, v93
	global_store_dwordx4 v[106:107], v[82:85], off offset:256
	v_and_b32_e32 v87, 0xffff0000, v136
	v_lshlrev_b32_e32 v88, 16, v137
	v_lshlrev_b32_e32 v82, 16, v134
	v_and_b32_e32 v83, 0xffff0000, v134
	v_lshlrev_b32_e32 v84, 16, v135
	v_and_b32_e32 v85, 0xffff0000, v135
	v_and_b32_e32 v89, 0xffff0000, v137
	v_pk_mul_f32 v[82:83], v[82:83], s[16:17] op_sel_hi:[1,0]
	v_pk_mul_f32 v[84:85], v[84:85], s[16:17] op_sel_hi:[1,0]
	v_pk_fma_f32 v[78:79], v[158:159], v[78:79], v[82:83]
	v_pk_fma_f32 v[80:81], v[156:157], v[80:81], v[84:85]
	v_pk_mul_f32 v[82:83], v[86:87], s[16:17] op_sel_hi:[1,0]
	v_pk_mul_f32 v[84:85], v[88:89], s[16:17] op_sel_hi:[1,0]
	v_lshl_add_u64 v[90:91], s[46:47], 0, v[170:171]
	v_pk_fma_f32 v[84:85], v[156:157], v[76:77], v[84:85]
	v_pk_fma_f32 v[76:77], v[158:159], v[74:75], v[82:83]
	v_lshl_add_u64 v[90:91], v[90:91], 0, v[164:165]
	v_cvt_pk_bf16_f32 v74, v78, v79
	v_cvt_pk_bf16_f32 v75, v80, v81
	v_cvt_pk_bf16_f32 v76, v76, v77
	v_cvt_pk_bf16_f32 v77, v84, v85
	global_store_dwordx4 v[90:91], v[74:77], off
	v_lshlrev_b32_e32 v78, 16, v132
	v_and_b32_e32 v79, 0xffff0000, v132
	v_lshlrev_b32_e32 v74, 16, v130
	v_and_b32_e32 v75, 0xffff0000, v130
	v_lshlrev_b32_e32 v76, 16, v131
	v_and_b32_e32 v77, 0xffff0000, v131
	v_lshlrev_b32_e32 v80, 16, v133
	v_and_b32_e32 v81, 0xffff0000, v133
	v_pk_mul_f32 v[74:75], v[74:75], s[16:17] op_sel_hi:[1,0]
	v_pk_mul_f32 v[76:77], v[76:77], s[16:17] op_sel_hi:[1,0]
	v_pk_fma_f32 v[70:71], v[158:159], v[70:71], v[74:75]
	v_pk_fma_f32 v[72:73], v[156:157], v[72:73], v[76:77]
	v_pk_mul_f32 v[74:75], v[78:79], s[16:17] op_sel_hi:[1,0]
	v_pk_mul_f32 v[76:77], v[80:81], s[16:17] op_sel_hi:[1,0]
	v_lshl_add_u64 v[102:103], v[168:169], 0, s[86:87]
	v_pk_fma_f32 v[76:77], v[156:157], v[68:69], v[76:77]
	v_pk_fma_f32 v[68:69], v[158:159], v[66:67], v[74:75]
	v_cvt_pk_bf16_f32 v66, v70, v71
	v_cvt_pk_bf16_f32 v67, v72, v73
	s_mov_b64 s[86:87], 0x50000
	v_cvt_pk_bf16_f32 v68, v68, v69
	v_cvt_pk_bf16_f32 v69, v76, v77
	global_store_dwordx4 v[90:91], v[66:69], off offset:256
	v_lshl_add_u64 v[104:105], v[168:169], 0, s[86:87]
	s_mov_b64 s[86:87], 0x58000
	v_lshl_add_u64 v[204:205], v[168:169], 0, s[86:87]
	s_nop 0
	v_lshl_add_u64 v[100:101], s[46:47], 0, v[100:101]
	v_lshl_add_u64 v[100:101], v[100:101], 0, v[164:165]
	s_mov_b64 s[86:87], -1
	s_waitcnt vmcnt(8)
; DI void store8(bf16_t* p, f32x4 a, f32x4 b) { u32x4 w; w.x = pk(a[0], a[1]); w.y = pk(a[2], a[3]); w.z = pk(b[0], b[1]); w.w = pk(b[2], b[3]); *(u32x4*)p = w; }
; DI void unpk8(const u32x4 w, f32x4& a, f32x4& b) { a = (f32x4){bflo(w.x), bfhi(w.x), bflo(w.y), bfhi(w.y)}; b = (f32x4){bflo(w.z), bfhi(w.z), bflo(w.w), bfhi(w.w)}; }
;     DI void operator()(AccRef acc, const Unit& u, int wr, int wc, int, int) const {
;     ...
;                 for (int bj = 0; bj < 2; ++bj) px[m][bj] = *(const u32x4*)(X + (size_t)(row0 + ai * 128 + m * 16) * D + col0 + bj * 128);
; #pragma unroll
;             for (int m = 0; m < 4; ++m)
; #pragma unroll
;                 for (int bj = 0; bj < 2; ++bj) { f32x4 x0, x1; unpk8(px[m][bj], x0, x1);
;                     store8(Z + (size_t)(row0 + ai * 128 + m * 16) * D + col0 + bj * 128, x0 * DN_ALPHA + acc[ai][bj][m][0] * s, x1 * DN_ALPHA + acc[ai][bj][m][1] * s); }
	v_lshlrev_b32_e32 v106, 16, v230
	v_and_b32_e32 v107, 0xffff0000, v230
	v_lshlrev_b32_e32 v230, 16, v231
	v_and_b32_e32 v231, 0xffff0000, v231
	v_lshlrev_b32_e32 v108, 16, v232
	v_and_b32_e32 v109, 0xffff0000, v232
	v_lshlrev_b32_e32 v232, 16, v233
	v_and_b32_e32 v233, 0xffff0000, v233
	v_pk_mul_f32 v[230:231], v[230:231], s[16:17] op_sel_hi:[1,0]
	v_pk_mul_f32 v[232:233], v[232:233], s[16:17] op_sel_hi:[1,0]
	v_pk_fma_f32 v[64:65], v[156:157], v[64:65], v[230:231]
	v_pk_mul_f32 v[230:231], v[108:109], s[16:17] op_sel_hi:[1,0]
	v_pk_mul_f32 v[106:107], v[106:107], s[16:17] op_sel_hi:[1,0]
	v_pk_fma_f32 v[232:233], v[156:157], v[60:61], v[232:233]
	v_pk_fma_f32 v[60:61], v[158:159], v[58:59], v[230:231]
	v_pk_fma_f32 v[62:63], v[158:159], v[62:63], v[106:107]
	s_nop 0
	v_cvt_pk_bf16_f32 v58, v62, v63
	v_cvt_pk_bf16_f32 v59, v64, v65
	v_cvt_pk_bf16_f32 v60, v60, v61
	v_cvt_pk_bf16_f32 v61, v232, v233
	global_store_dwordx4 v[100:101], v[58:61], off
	v_lshlrev_b32_e32 v62, 16, v236
	v_and_b32_e32 v63, 0xffff0000, v236
	v_lshlrev_b32_e32 v58, 16, v234
	v_and_b32_e32 v59, 0xffff0000, v234
	v_lshlrev_b32_e32 v60, 16, v235
	v_and_b32_e32 v61, 0xffff0000, v235
	v_lshlrev_b32_e32 v64, 16, v237
	v_and_b32_e32 v65, 0xffff0000, v237
	v_pk_mul_f32 v[58:59], v[58:59], s[16:17] op_sel_hi:[1,0]
	v_pk_mul_f32 v[60:61], v[60:61], s[16:17] op_sel_hi:[1,0]
	v_pk_fma_f32 v[54:55], v[158:159], v[54:55], v[58:59]
	v_pk_fma_f32 v[56:57], v[156:157], v[56:57], v[60:61]
	v_pk_mul_f32 v[58:59], v[62:63], s[16:17] op_sel_hi:[1,0]
	v_pk_mul_f32 v[60:61], v[64:65], s[16:17] op_sel_hi:[1,0]
	s_nop 0
	v_pk_fma_f32 v[60:61], v[156:157], v[52:53], v[60:61]
	v_pk_fma_f32 v[52:53], v[158:159], v[50:51], v[58:59]
	v_cvt_pk_bf16_f32 v50, v54, v55
	v_cvt_pk_bf16_f32 v51, v56, v57
	v_lshlrev_b32_e32 v54, 16, v240
	v_cvt_pk_bf16_f32 v52, v52, v53
	v_cvt_pk_bf16_f32 v53, v60, v61
	global_store_dwordx4 v[100:101], v[50:53], off offset:256
	v_and_b32_e32 v55, 0xffff0000, v240
	v_lshlrev_b32_e32 v56, 16, v241
	v_lshlrev_b32_e32 v50, 16, v238
	v_and_b32_e32 v51, 0xffff0000, v238
	v_lshlrev_b32_e32 v52, 16, v239
	v_and_b32_e32 v53, 0xffff0000, v239
	v_and_b32_e32 v57, 0xffff0000, v241
	v_pk_mul_f32 v[50:51], v[50:51], s[16:17] op_sel_hi:[1,0]
	v_pk_mul_f32 v[52:53], v[52:53], s[16:17] op_sel_hi:[1,0]
	v_pk_fma_f32 v[46:47], v[158:159], v[46:47], v[50:51]
	v_pk_fma_f32 v[48:49], v[156:157], v[48:49], v[52:53]
	v_pk_mul_f32 v[50:51], v[54:55], s[16:17] op_sel_hi:[1,0]
	v_pk_mul_f32 v[52:53], v[56:57], s[16:17] op_sel_hi:[1,0]
	v_lshl_add_u64 v[58:59], s[46:47], 0, v[102:103]
	v_pk_fma_f32 v[52:53], v[156:157], v[44:45], v[52:53]
	v_pk_fma_f32 v[44:45], v[158:159], v[42:43], v[50:51]
	v_lshl_add_u64 v[58:59], v[58:59], 0, v[164:165]
	v_cvt_pk_bf16_f32 v42, v46, v47
	v_cvt_pk_bf16_f32 v43, v48, v49
	v_cvt_pk_bf16_f32 v44, v44, v45
	v_cvt_pk_bf16_f32 v45, v52, v53
	global_store_dwordx4 v[58:59], v[42:45], off
	v_lshlrev_b32_e32 v46, 16, v244
	v_and_b32_e32 v47, 0xffff0000, v244
	v_lshlrev_b32_e32 v42, 16, v242
	v_and_b32_e32 v43, 0xffff0000, v242
	v_lshlrev_b32_e32 v44, 16, v243
	v_and_b32_e32 v45, 0xffff0000, v243
	v_lshlrev_b32_e32 v48, 16, v245
	v_and_b32_e32 v49, 0xffff0000, v245
	v_pk_mul_f32 v[42:43], v[42:43], s[16:17] op_sel_hi:[1,0]
	v_pk_mul_f32 v[44:45], v[44:45], s[16:17] op_sel_hi:[1,0]
	v_pk_fma_f32 v[38:39], v[158:159], v[38:39], v[42:43]
	v_pk_fma_f32 v[40:41], v[156:157], v[40:41], v[44:45]
	v_pk_mul_f32 v[42:43], v[46:47], s[16:17] op_sel_hi:[1,0]
	v_pk_mul_f32 v[44:45], v[48:49], s[16:17] op_sel_hi:[1,0]
	s_nop 0
	v_pk_fma_f32 v[44:45], v[156:157], v[36:37], v[44:45]
	v_pk_fma_f32 v[36:37], v[158:159], v[34:35], v[42:43]
	v_cvt_pk_bf16_f32 v34, v38, v39
	v_cvt_pk_bf16_f32 v35, v40, v41
	v_lshlrev_b32_e32 v38, 16, v248
	v_cvt_pk_bf16_f32 v36, v36, v37
	v_cvt_pk_bf16_f32 v37, v44, v45
	global_store_dwordx4 v[58:59], v[34:37], off offset:256
	v_and_b32_e32 v39, 0xffff0000, v248
; DI void store8(bf16_t* p, f32x4 a, f32x4 b) { u32x4 w; w.x = pk(a[0], a[1]); w.y = pk(a[2], a[3]); w.z = pk(b[0], b[1]); w.w = pk(b[2], b[3]); *(u32x4*)p = w; }
; DI void unpk8(const u32x4 w, f32x4& a, f32x4& b) { a = (f32x4){bflo(w.x), bfhi(w.x), bflo(w.y), bfhi(w.y)}; b = (f32x4){bflo(w.z), bfhi(w.z), bflo(w.w), bfhi(w.w)}; }
;     DI void operator()(AccRef acc, const Unit& u, int wr, int wc, int, int) const {
;     ...
;             for (int m = 0; m < 4; ++m)
; #pragma unroll
;                 for (int bj = 0; bj < 2; ++bj) { f32x4 x0, x1; unpk8(px[m][bj], x0, x1);
;                     store8(Z + (size_t)(row0 + ai * 128 + m * 16) * D + col0 + bj * 128, x0 * DN_ALPHA + acc[ai][bj][m][0] * s, x1 * DN_ALPHA + acc[ai][bj][m][1] * s); }
;             asm volatile("" ::: "memory");
;         }
	v_lshlrev_b32_e32 v40, 16, v249
	v_lshlrev_b32_e32 v34, 16, v246
	v_and_b32_e32 v35, 0xffff0000, v246
	v_lshlrev_b32_e32 v36, 16, v247
	v_and_b32_e32 v37, 0xffff0000, v247
	v_and_b32_e32 v41, 0xffff0000, v249
	v_pk_mul_f32 v[34:35], v[34:35], s[16:17] op_sel_hi:[1,0]
	v_pk_mul_f32 v[36:37], v[36:37], s[16:17] op_sel_hi:[1,0]
	v_pk_fma_f32 v[30:31], v[158:159], v[30:31], v[34:35]
	v_pk_fma_f32 v[32:33], v[156:157], v[32:33], v[36:37]
	v_pk_mul_f32 v[34:35], v[38:39], s[16:17] op_sel_hi:[1,0]
	v_pk_mul_f32 v[36:37], v[40:41], s[16:17] op_sel_hi:[1,0]
	v_lshl_add_u64 v[42:43], s[46:47], 0, v[104:105]
	v_pk_fma_f32 v[36:37], v[156:157], v[28:29], v[36:37]
	v_pk_fma_f32 v[28:29], v[158:159], v[26:27], v[34:35]
	v_lshl_add_u64 v[42:43], v[42:43], 0, v[164:165]
	v_cvt_pk_bf16_f32 v26, v30, v31
	v_cvt_pk_bf16_f32 v27, v32, v33
	v_cvt_pk_bf16_f32 v28, v28, v29
	v_cvt_pk_bf16_f32 v29, v36, v37
	global_store_dwordx4 v[42:43], v[26:29], off
	v_lshlrev_b32_e32 v30, 16, v210
	v_and_b32_e32 v31, 0xffff0000, v210
	v_lshlrev_b32_e32 v26, 16, v208
	v_and_b32_e32 v27, 0xffff0000, v208
	v_lshlrev_b32_e32 v28, 16, v209
	v_and_b32_e32 v29, 0xffff0000, v209
	v_lshlrev_b32_e32 v32, 16, v211
	v_and_b32_e32 v33, 0xffff0000, v211
	v_pk_mul_f32 v[26:27], v[26:27], s[16:17] op_sel_hi:[1,0]
	v_pk_mul_f32 v[28:29], v[28:29], s[16:17] op_sel_hi:[1,0]
	v_pk_fma_f32 v[22:23], v[158:159], v[22:23], v[26:27]
	v_pk_fma_f32 v[24:25], v[156:157], v[24:25], v[28:29]
	v_pk_mul_f32 v[26:27], v[30:31], s[16:17] op_sel_hi:[1,0]
	v_pk_mul_f32 v[28:29], v[32:33], s[16:17] op_sel_hi:[1,0]
	s_nop 0
	v_pk_fma_f32 v[28:29], v[156:157], v[20:21], v[28:29]
	v_pk_fma_f32 v[20:21], v[158:159], v[18:19], v[26:27]
	v_cvt_pk_bf16_f32 v18, v22, v23
	v_cvt_pk_bf16_f32 v19, v24, v25
	v_lshlrev_b32_e32 v22, 16, v198
	v_cvt_pk_bf16_f32 v20, v20, v21
	v_cvt_pk_bf16_f32 v21, v28, v29
	global_store_dwordx4 v[42:43], v[18:21], off offset:256
	v_and_b32_e32 v23, 0xffff0000, v198
	v_lshlrev_b32_e32 v24, 16, v199
	v_lshlrev_b32_e32 v18, 16, v196
	v_and_b32_e32 v19, 0xffff0000, v196
	v_lshlrev_b32_e32 v20, 16, v197
	v_and_b32_e32 v21, 0xffff0000, v197
	v_and_b32_e32 v25, 0xffff0000, v199
	v_pk_mul_f32 v[18:19], v[18:19], s[16:17] op_sel_hi:[1,0]
	v_pk_mul_f32 v[20:21], v[20:21], s[16:17] op_sel_hi:[1,0]
	v_pk_fma_f32 v[14:15], v[158:159], v[14:15], v[18:19]
	v_pk_fma_f32 v[16:17], v[156:157], v[16:17], v[20:21]
	v_pk_mul_f32 v[18:19], v[22:23], s[16:17] op_sel_hi:[1,0]
	v_pk_mul_f32 v[20:21], v[24:25], s[16:17] op_sel_hi:[1,0]
	v_lshl_add_u64 v[26:27], s[46:47], 0, v[204:205]
	v_pk_fma_f32 v[20:21], v[156:157], v[12:13], v[20:21]
	v_pk_fma_f32 v[12:13], v[158:159], v[10:11], v[18:19]
	v_lshl_add_u64 v[26:27], v[26:27], 0, v[164:165]
	v_cvt_pk_bf16_f32 v10, v14, v15
	v_cvt_pk_bf16_f32 v11, v16, v17
	v_cvt_pk_bf16_f32 v12, v12, v13
	v_cvt_pk_bf16_f32 v13, v20, v21
	global_store_dwordx4 v[26:27], v[10:13], off
	v_lshlrev_b32_e32 v14, 16, v202
	v_and_b32_e32 v15, 0xffff0000, v202
	v_lshlrev_b32_e32 v10, 16, v200
	v_and_b32_e32 v11, 0xffff0000, v200
	v_lshlrev_b32_e32 v12, 16, v201
	v_and_b32_e32 v13, 0xffff0000, v201
	v_lshlrev_b32_e32 v16, 16, v203
	v_and_b32_e32 v17, 0xffff0000, v203
	v_pk_mul_f32 v[10:11], v[10:11], s[16:17] op_sel_hi:[1,0]
	v_pk_mul_f32 v[12:13], v[12:13], s[16:17] op_sel_hi:[1,0]
	v_pk_fma_f32 v[6:7], v[158:159], v[6:7], v[10:11]
	v_pk_fma_f32 v[8:9], v[156:157], v[8:9], v[12:13]
	v_pk_mul_f32 v[10:11], v[14:15], s[16:17] op_sel_hi:[1,0]
	v_pk_mul_f32 v[12:13], v[16:17], s[16:17] op_sel_hi:[1,0]
	s_nop 0
	v_pk_fma_f32 v[12:13], v[156:157], v[4:5], v[12:13]
	v_pk_fma_f32 v[4:5], v[158:159], v[2:3], v[10:11]
	v_cvt_pk_bf16_f32 v2, v6, v7
	v_cvt_pk_bf16_f32 v3, v8, v9
	s_nop 0
	v_cvt_pk_bf16_f32 v4, v4, v5
	v_cvt_pk_bf16_f32 v5, v12, v13
	global_store_dwordx4 v[26:27], v[2:5], off offset:256
	s_cbranch_vccnz .LBB0_672
	s_andn2_b64 vcc, exec, s[44:45]
	s_cbranch_vccnz .LBB0_671
	s_barrier
	s_branch .LBB0_671
